# gla_C carry MFMA global loads ring-prefetched (16 in flight); gla_item stage2/stage6 LDS reads software-pipelined
# speedup vs baseline: 1.0122x; 1.0036x over previous
; #define LAS __attribute__((address_space(3)))
; __device__ __forceinline__ float bf2f(unsigned short b) { return __uint_as_float(((unsigned)b) << 16); }
; __device__ __forceinline__ u32x4 pack8(const float (&f)[8]) { u32x4 w; w.x = cvt_pk_bf16(f[0], f[1]); w.y = cvt_pk_bf16(f[2], f[3]); w.z = cvt_pk_bf16(f[4], f[5]); w.w = cvt_pk_bf16(f[6], f[7]); return w; }
; __device__ void gla_C(const Params& P, int l, int item, LAS unsigned char* lds) {
;     ...
;     bf16x8 Sb[2];
; #pragma unroll
;     for (int ks = 0; ks < 2; ++ks) Sb[ks] = as_bf16x8(pack8(Sin[ks]));
;     const int row0 = b * 2048 + seg * 256;
;     {
; #pragma unroll
;         for (int i = 0; i < 8; ++i) { const int p = tid + i * NTHR, r = p >> 4, sg = p & 15; *(LAS u32x4*)(OT + r * 272 + sg * 16) = ov[i]; *(LAS u32x2*)(GTL + r * 264 + sg * 16) = (u32x2){gv[i].x, gv[i].y}; *(LAS u32x2*)(GTL + r * 264 + sg * 16 + 8) = (u32x2){gv[i].z, gv[i].w}; }
;     }
;     __syncthreads();
;     f32x4 O[16];
; #pragma unroll
;     for (int rt = 0; rt < 16; ++rt) {
; #pragma unroll
;         for (int jj = 0; jj < 4; ++jj) O[rt][jj] = bf2f(*(const LAS unsigned short*)(OT + (rt * 16 + 4 * g + jj) * 272 + (16 * w + c) * 2));
;         if (seg > 0) {
; #pragma unroll
;             for (int ks = 0; ks < 2; ++ks) { const bf16x8 a = as_bf16x8(*(const u32x4*)(Z + (size_t)(row0 + rt * 16 + c) * ZC + ZQ + h * 64 + ks * 32 + 8 * g)); O[rt] = __builtin_amdgcn_mfma_f32_16x16x32_bf16(a, Sb[ks], O[rt], 0, 0, 0); }
.LBB0_380:
	s_movk_i32 s8, 0x110
	v_add_u32_e32 v75, 0, v100
	v_readlane_b32 s5, v255, 12
	v_mul_lo_u32 v83, v158, s8
	v_add_u32_e32 v76, v75, v83
	v_add_u32_e32 v74, s5, v100
	s_movk_i32 s5, 0x108
	s_waitcnt lgkmcnt(1)
	v_cvt_pk_bf16_f32 v70, v167, v104
	v_cvt_pk_bf16_f32 v71, v105, v108
	v_cvt_pk_bf16_f32 v72, v109, v114
	v_cvt_pk_bf16_f32 v73, v115, v166
	v_cvt_pk_bf16_f32 v66, v102, v103
	v_cvt_pk_bf16_f32 v67, v106, v107
	s_waitcnt lgkmcnt(0)
	v_cvt_pk_bf16_f32 v68, v110, v111
	v_cvt_pk_bf16_f32 v69, v112, v113
	s_waitcnt vmcnt(15)
	ds_write_b128 v76, v[18:21] offset:8192
	v_mad_u64_u32 v[18:19], s[6:7], v158, s5, v[74:75]
	v_mul_lo_u32 v82, v159, s8
	s_waitcnt vmcnt(14)
	ds_write2_b64 v18, v[2:3], v[4:5] offset1:1
	v_add_u32_e32 v2, v75, v82
	s_waitcnt vmcnt(13)
	ds_write_b128 v2, v[10:13] offset:8192
	v_mad_u64_u32 v[2:3], s[6:7], v159, s5, v[74:75]
	v_mul_lo_u32 v81, v160, s8
	s_waitcnt vmcnt(12)
	ds_write2_b64 v2, v[6:7], v[8:9] offset1:1
	v_add_u32_e32 v2, v75, v81
	s_waitcnt vmcnt(11)
	ds_write_b128 v2, v[22:25] offset:8192
	v_mad_u64_u32 v[2:3], s[6:7], v160, s5, v[74:75]
	v_mul_lo_u32 v80, v161, s8
	s_waitcnt vmcnt(10)
	ds_write2_b64 v2, v[14:15], v[16:17] offset1:1
	v_add_u32_e32 v2, v75, v80
	s_waitcnt vmcnt(9)
	ds_write_b128 v2, v[30:33] offset:8192
	v_mad_u64_u32 v[2:3], s[6:7], v161, s5, v[74:75]
	v_mul_lo_u32 v79, v162, s8
	s_waitcnt vmcnt(8)
	ds_write2_b64 v2, v[26:27], v[28:29] offset1:1
	v_add_u32_e32 v2, v75, v79
	s_waitcnt vmcnt(7)
	ds_write_b128 v2, v[38:41] offset:8192
	v_mad_u64_u32 v[2:3], s[6:7], v162, s5, v[74:75]
	v_mul_lo_u32 v78, v163, s8
	s_waitcnt vmcnt(6)
	ds_write2_b64 v2, v[34:35], v[36:37] offset1:1
	v_add_u32_e32 v2, v75, v78
	s_waitcnt vmcnt(5)
	ds_write_b128 v2, v[46:49] offset:8192
	v_mad_u64_u32 v[2:3], s[6:7], v163, s5, v[74:75]
	v_mul_lo_u32 v77, v164, s8
	s_waitcnt vmcnt(4)
	ds_write2_b64 v2, v[42:43], v[44:45] offset1:1
	v_add_u32_e32 v2, v75, v77
	s_waitcnt vmcnt(3)
	ds_write_b128 v2, v[58:61] offset:8192
	v_mad_u64_u32 v[2:3], s[6:7], v164, s5, v[74:75]
	v_mul_lo_u32 v76, v165, s8
	s_waitcnt vmcnt(2)
	ds_write2_b64 v2, v[50:51], v[52:53] offset1:1
	v_add_u32_e32 v2, v75, v76
	s_waitcnt vmcnt(1)
	ds_write_b128 v2, v[62:65] offset:8192
	v_mad_u64_u32 v[2:3], s[6:7], v165, s5, v[74:75]
	s_waitcnt vmcnt(0)
	ds_write2_b64 v2, v[54:55], v[56:57] offset1:1
	v_or_b32_e32 v2, s30, v97
	v_lshlrev_b32_e32 v102, 2, v157
	v_lshlrev_b32_e32 v100, 1, v2
	v_add_u32_e32 v95, 0, v100
	s_movk_i32 s6, 0x440
	v_or_b32_e32 v96, 1, v102
	v_mad_u32_u24 v4, v157, s6, v95
	v_mad_u32_u24 v5, v96, s8, v95
	v_mad_u32_u24 v2, v96, s8, v231
	s_waitcnt lgkmcnt(0)
	s_barrier
	v_add_u32_e32 v3, v95, v2
	ds_read_u16 v4, v4 offset:8192
	ds_read_u16 v6, v5 offset:8192
	ds_read_u16 v5, v5 offset:8464
	ds_read_u16 v7, v3 offset:8192
	v_or_b32_e32 v103, s4, v97
	s_lshl_b64 s[4:5], s[20:21], 1
	s_add_u32 s4, s28, s4
	s_addc_u32 s5, s29, s5
	v_lshlrev_b32_e32 v194, 1, v98
	s_movk_i32 s9, 0x108
	v_lshl_add_u64 v[74:75], s[4:5], 0, v[194:195]
	s_waitcnt lgkmcnt(3)
	v_lshlrev_b32_e32 v62, 16, v4
	s_waitcnt lgkmcnt(2)
	v_lshlrev_b32_e32 v63, 16, v6
	s_waitcnt lgkmcnt(1)
	v_lshlrev_b32_e32 v64, 16, v5
	s_waitcnt lgkmcnt(0)
	v_lshlrev_b32_e32 v65, 16, v7
	s_and_b64 vcc, exec, s[0:1]
	s_cbranch_vccz .LBB0_382
	v_or_b32_e32 v184, 0, v103
	v_mad_i64_i32 v[168:169], s[4:5], v184, s25, v[74:75]
	global_load_dwordx4 v[116:119], v[168:169], off
	global_load_dwordx4 v[120:123], v[168:169], off offset:64
	v_or_b32_e32 v185, 16, v103
	v_mad_i64_i32 v[170:171], s[4:5], v185, s25, v[74:75]
	global_load_dwordx4 v[124:127], v[170:171], off
	global_load_dwordx4 v[128:131], v[170:171], off offset:64
	v_or_b32_e32 v186, 32, v103
	v_mad_i64_i32 v[172:173], s[4:5], v186, s25, v[74:75]
	global_load_dwordx4 v[132:135], v[172:173], off
	global_load_dwordx4 v[136:139], v[172:173], off offset:64
	v_or_b32_e32 v187, 48, v103
	v_mad_i64_i32 v[174:175], s[4:5], v187, s25, v[74:75]
	global_load_dwordx4 v[140:143], v[174:175], off
	global_load_dwordx4 v[144:147], v[174:175], off offset:64
	v_or_b32_e32 v188, 64, v103
	v_mad_i64_i32 v[176:177], s[4:5], v188, s25, v[74:75]
	global_load_dwordx4 v[204:207], v[176:177], off
	global_load_dwordx4 v[208:211], v[176:177], off offset:64
	v_or_b32_e32 v189, 80, v103
	v_mad_i64_i32 v[178:179], s[4:5], v189, s25, v[74:75]
	global_load_dwordx4 v[212:215], v[178:179], off
	global_load_dwordx4 v[216:219], v[178:179], off offset:64
	v_or_b32_e32 v190, 96, v103
	v_mad_i64_i32 v[180:181], s[4:5], v190, s25, v[74:75]
	global_load_dwordx4 v[220:223], v[180:181], off
	global_load_dwordx4 v[224:227], v[180:181], off offset:64
	v_or_b32_e32 v191, 112, v103
	v_mad_i64_i32 v[182:183], s[4:5], v191, s25, v[74:75]
	global_load_dwordx4 v[236:239], v[182:183], off
	global_load_dwordx4 v[240:243], v[182:183], off offset:64
	s_waitcnt vmcnt(15)
	v_mfma_f32_16x16x32_bf16 v[4:7], v[116:119], v[70:73], v[62:65]
	s_waitcnt vmcnt(14)
	v_mfma_f32_16x16x32_bf16 v[62:65], v[120:123], v[66:69], v[4:7]
	v_or_b32_e32 v184, 128, v103
	v_mad_i64_i32 v[168:169], s[4:5], v184, s25, v[74:75]
	global_load_dwordx4 v[116:119], v[168:169], off
	global_load_dwordx4 v[120:123], v[168:169], off offset:64
; #define LAS __attribute__((address_space(3)))
; __device__ __forceinline__ float bf2f(unsigned short b) { return __uint_as_float(((unsigned)b) << 16); }
; __device__ void gla_C(const Params& P, int l, int item, LAS unsigned char* lds) {
;     ...
;     for (int rt = 0; rt < 16; ++rt) {
; #pragma unroll
;         for (int jj = 0; jj < 4; ++jj) O[rt][jj] = bf2f(*(const LAS unsigned short*)(OT + (rt * 16 + 4 * g + jj) * 272 + (16 * w + c) * 2));
;         if (seg > 0) {
; #pragma unroll
;             for (int ks = 0; ks < 2; ++ks) { const bf16x8 a = as_bf16x8(*(const u32x4*)(Z + (size_t)(row0 + rt * 16 + c) * ZC + ZQ + h * 64 + ks * 32 + 8 * g)); O[rt] = __builtin_amdgcn_mfma_f32_16x16x32_bf16(a, Sb[ks], O[rt], 0, 0, 0); }
;         }
.LBB0_382:
	s_nop 4
	v_add_u32_e32 v4, 0xff0, v2
	v_add_u32_e32 v2, 0x1100, v2
	v_add_u32_e32 v94, v95, v4
	ds_read_u16 v4, v3 offset:11728
	ds_read_u16 v5, v3 offset:12000
	ds_read_u16 v6, v94 offset:8192
	v_add_u32_e32 v3, v95, v2
	ds_read_u16 v7, v3 offset:8192
	s_waitcnt lgkmcnt(3)
	v_lshlrev_b32_e32 v58, 16, v4
	v_cndmask_b32_e64 v4, 0, 1, s[0:1]
	s_waitcnt lgkmcnt(2)
	v_lshlrev_b32_e32 v59, 16, v5
	s_waitcnt lgkmcnt(1)
	v_lshlrev_b32_e32 v60, 16, v6
	v_cmp_ne_u32_e64 s[38:39], 1, v4
	s_andn2_b64 vcc, exec, s[0:1]
	s_waitcnt lgkmcnt(0)
	v_lshlrev_b32_e32 v61, 16, v7
	s_cbranch_vccnz .LBB0_384
	s_waitcnt vmcnt(15)
	v_mfma_f32_16x16x32_bf16 v[4:7], v[124:127], v[70:73], v[58:61]
	s_waitcnt vmcnt(14)
	v_mfma_f32_16x16x32_bf16 v[58:61], v[128:131], v[66:69], v[4:7]
	v_or_b32_e32 v185, 144, v103
	v_mad_i64_i32 v[170:171], s[0:1], v185, s25, v[74:75]
	global_load_dwordx4 v[124:127], v[170:171], off
	global_load_dwordx4 v[128:131], v[170:171], off offset:64
.LBB0_384:
	v_add_u32_e32 v2, 0x1100, v2
	v_add_u32_e32 v93, v95, v2
	s_nop 2
	ds_read_u16 v4, v3 offset:11728
	ds_read_u16 v5, v3 offset:12000
	ds_read_u16 v3, v3 offset:12272
	ds_read_u16 v6, v93 offset:8192
	s_and_b64 vcc, exec, s[38:39]
	s_waitcnt lgkmcnt(3)
	v_lshlrev_b32_e32 v54, 16, v4
	s_waitcnt lgkmcnt(2)
	v_lshlrev_b32_e32 v55, 16, v5
	s_waitcnt lgkmcnt(1)
	v_lshlrev_b32_e32 v56, 16, v3
	s_waitcnt lgkmcnt(0)
	v_lshlrev_b32_e32 v57, 16, v6
	s_cbranch_vccnz .LBB0_386
	s_waitcnt vmcnt(15)
	v_mfma_f32_16x16x32_bf16 v[4:7], v[132:135], v[70:73], v[54:57]
	s_waitcnt vmcnt(14)
	v_mfma_f32_16x16x32_bf16 v[54:57], v[136:139], v[66:69], v[4:7]
	v_or_b32_e32 v186, 160, v103
	v_mad_i64_i32 v[172:173], s[0:1], v186, s25, v[74:75]
	global_load_dwordx4 v[132:135], v[172:173], off
	global_load_dwordx4 v[136:139], v[172:173], off offset:64
.LBB0_386:
	v_add_u32_e32 v2, 0x1100, v2
	s_nop 3
	v_add_u32_e32 v6, v95, v2
	ds_read_u16 v3, v93 offset:11728
	ds_read_u16 v4, v93 offset:12000
	ds_read_u16 v5, v93 offset:12272
	ds_read_u16 v6, v6 offset:8192
	s_and_b64 vcc, exec, s[38:39]
	s_waitcnt lgkmcnt(3)
	v_lshlrev_b32_e32 v50, 16, v3
	s_waitcnt lgkmcnt(2)
	v_lshlrev_b32_e32 v51, 16, v4
	s_waitcnt lgkmcnt(1)
	v_lshlrev_b32_e32 v52, 16, v5
	s_waitcnt lgkmcnt(0)
	v_lshlrev_b32_e32 v53, 16, v6
	s_cbranch_vccnz .LBB0_388
	s_waitcnt vmcnt(15)
	v_mfma_f32_16x16x32_bf16 v[4:7], v[140:143], v[70:73], v[50:53]
	s_waitcnt vmcnt(14)
	v_mfma_f32_16x16x32_bf16 v[50:53], v[144:147], v[66:69], v[4:7]
	v_or_b32_e32 v187, 176, v103
	v_mad_i64_i32 v[174:175], s[0:1], v187, s25, v[74:75]
	global_load_dwordx4 v[140:143], v[174:175], off
	global_load_dwordx4 v[144:147], v[174:175], off offset:64
.LBB0_388:
	v_add_u32_e32 v3, 0xdd0, v2
	v_add_u32_e32 v2, 0x1100, v2
	v_add_u32_e32 v92, v95, v3
	v_add_u32_e32 v3, v95, v2
	s_nop 0
	ds_read_u16 v4, v92 offset:8192
	ds_read_u16 v5, v92 offset:8464
	ds_read_u16 v6, v92 offset:8736
	ds_read_u16 v7, v3 offset:8192
	s_and_b64 vcc, exec, s[38:39]
	s_waitcnt lgkmcnt(3)
	v_lshlrev_b32_e32 v46, 16, v4
	s_waitcnt lgkmcnt(2)
	v_lshlrev_b32_e32 v47, 16, v5
	s_waitcnt lgkmcnt(1)
	v_lshlrev_b32_e32 v48, 16, v6
	s_waitcnt lgkmcnt(0)
	v_lshlrev_b32_e32 v49, 16, v7
	s_cbranch_vccnz .LBB0_390
	s_waitcnt vmcnt(15)
	v_mfma_f32_16x16x32_bf16 v[4:7], v[204:207], v[70:73], v[46:49]
	s_waitcnt vmcnt(14)
	v_mfma_f32_16x16x32_bf16 v[46:49], v[208:211], v[66:69], v[4:7]
	v_or_b32_e32 v188, 192, v103
	v_mad_i64_i32 v[176:177], s[0:1], v188, s25, v[74:75]
	global_load_dwordx4 v[204:207], v[176:177], off
	global_load_dwordx4 v[208:211], v[176:177], off offset:64
.LBB0_390:
	s_nop 4
	v_add_u32_e32 v4, 0xee0, v2
	v_add_u32_e32 v2, 0x1100, v2
	v_add_u32_e32 v91, v95, v4
	ds_read_u16 v4, v3 offset:11728
	ds_read_u16 v5, v91 offset:8192
	ds_read_u16 v6, v91 offset:8464
	v_add_u32_e32 v3, v95, v2
	ds_read_u16 v7, v3 offset:8192
	s_waitcnt lgkmcnt(3)
	v_lshlrev_b32_e32 v42, 16, v4
	s_waitcnt lgkmcnt(2)
	v_lshlrev_b32_e32 v43, 16, v5
	s_waitcnt lgkmcnt(1)
	v_lshlrev_b32_e32 v44, 16, v6
	s_and_b64 vcc, exec, s[38:39]
	s_waitcnt lgkmcnt(0)
	v_lshlrev_b32_e32 v45, 16, v7
	s_cbranch_vccnz .LBB0_392
	s_waitcnt vmcnt(15)
	v_mfma_f32_16x16x32_bf16 v[4:7], v[212:215], v[70:73], v[42:45]
	s_waitcnt vmcnt(14)
	v_mfma_f32_16x16x32_bf16 v[42:45], v[216:219], v[66:69], v[4:7]
	v_or_b32_e32 v189, 208, v103
	v_mad_i64_i32 v[178:179], s[0:1], v189, s25, v[74:75]
	global_load_dwordx4 v[212:215], v[178:179], off
	global_load_dwordx4 v[216:219], v[178:179], off offset:64
.LBB0_392:
	s_nop 4
	v_add_u32_e32 v4, 0xff0, v2
	v_add_u32_e32 v2, 0x1100, v2
	v_add_u32_e32 v90, v95, v4
	ds_read_u16 v4, v3 offset:11728
	ds_read_u16 v5, v3 offset:12000
	ds_read_u16 v6, v90 offset:8192
	v_add_u32_e32 v3, v95, v2
	ds_read_u16 v7, v3 offset:8192
	s_waitcnt lgkmcnt(3)
	v_lshlrev_b32_e32 v38, 16, v4
	s_waitcnt lgkmcnt(2)
	v_lshlrev_b32_e32 v39, 16, v5
	s_waitcnt lgkmcnt(1)
	v_lshlrev_b32_e32 v40, 16, v6
	s_and_b64 vcc, exec, s[38:39]
	s_waitcnt lgkmcnt(0)
	v_lshlrev_b32_e32 v41, 16, v7
	s_cbranch_vccnz .LBB0_394
	s_waitcnt vmcnt(15)
	v_mfma_f32_16x16x32_bf16 v[4:7], v[220:223], v[70:73], v[38:41]
	s_waitcnt vmcnt(14)
	v_mfma_f32_16x16x32_bf16 v[38:41], v[224:227], v[66:69], v[4:7]
	v_or_b32_e32 v190, 224, v103
	v_mad_i64_i32 v[180:181], s[0:1], v190, s25, v[74:75]
	global_load_dwordx4 v[220:223], v[180:181], off
	global_load_dwordx4 v[224:227], v[180:181], off offset:64
; #define LAS __attribute__((address_space(3)))
; __device__ __forceinline__ float bf2f(unsigned short b) { return __uint_as_float(((unsigned)b) << 16); }
; __device__ void gla_C(const Params& P, int l, int item, LAS unsigned char* lds) {
;     ...
;     for (int rt = 0; rt < 16; ++rt) {
; #pragma unroll
;         for (int jj = 0; jj < 4; ++jj) O[rt][jj] = bf2f(*(const LAS unsigned short*)(OT + (rt * 16 + 4 * g + jj) * 272 + (16 * w + c) * 2));
;         if (seg > 0) {
; #pragma unroll
;             for (int ks = 0; ks < 2; ++ks) { const bf16x8 a = as_bf16x8(*(const u32x4*)(Z + (size_t)(row0 + rt * 16 + c) * ZC + ZQ + h * 64 + ks * 32 + 8 * g)); O[rt] = __builtin_amdgcn_mfma_f32_16x16x32_bf16(a, Sb[ks], O[rt], 0, 0, 0); }
;         }
.LBB0_394:
	v_add_u32_e32 v2, 0x1100, v2
	v_add_u32_e32 v89, v95, v2
	s_nop 2
	ds_read_u16 v4, v3 offset:11728
	ds_read_u16 v5, v3 offset:12000
	ds_read_u16 v3, v3 offset:12272
	ds_read_u16 v6, v89 offset:8192
	s_and_b64 vcc, exec, s[38:39]
	s_waitcnt lgkmcnt(3)
	v_lshlrev_b32_e32 v34, 16, v4
	s_waitcnt lgkmcnt(2)
	v_lshlrev_b32_e32 v35, 16, v5
	s_waitcnt lgkmcnt(1)
	v_lshlrev_b32_e32 v36, 16, v3
	s_waitcnt lgkmcnt(0)
	v_lshlrev_b32_e32 v37, 16, v6
	s_cbranch_vccnz .LBB0_396
	s_waitcnt vmcnt(15)
	v_mfma_f32_16x16x32_bf16 v[4:7], v[236:239], v[70:73], v[34:37]
	s_waitcnt vmcnt(14)
	v_mfma_f32_16x16x32_bf16 v[34:37], v[240:243], v[66:69], v[4:7]
	v_or_b32_e32 v191, 240, v103
	v_mad_i64_i32 v[182:183], s[0:1], v191, s25, v[74:75]
	global_load_dwordx4 v[236:239], v[182:183], off
	global_load_dwordx4 v[240:243], v[182:183], off offset:64
.LBB0_396:
	v_add_u32_e32 v2, 0x1100, v2
	s_nop 3
	v_add_u32_e32 v6, v95, v2
	ds_read_u16 v3, v89 offset:11728
	ds_read_u16 v4, v89 offset:12000
	ds_read_u16 v5, v89 offset:12272
	ds_read_u16 v6, v6 offset:8192
	s_and_b64 vcc, exec, s[38:39]
	s_waitcnt lgkmcnt(3)
	v_lshlrev_b32_e32 v30, 16, v3
	s_waitcnt lgkmcnt(2)
	v_lshlrev_b32_e32 v31, 16, v4
	s_waitcnt lgkmcnt(1)
	v_lshlrev_b32_e32 v32, 16, v5
	s_waitcnt lgkmcnt(0)
	v_lshlrev_b32_e32 v33, 16, v6
	s_cbranch_vccnz .LBB0_398
	s_waitcnt vmcnt(15)
	v_mfma_f32_16x16x32_bf16 v[4:7], v[116:119], v[70:73], v[30:33]
	s_waitcnt vmcnt(14)
	v_mfma_f32_16x16x32_bf16 v[30:33], v[120:123], v[66:69], v[4:7]
.LBB0_398:
	v_add_u32_e32 v3, 0xdd0, v2
	v_add_u32_e32 v2, 0x1100, v2
	v_add_u32_e32 v88, v95, v3
	v_add_u32_e32 v3, v95, v2
	s_nop 0
	ds_read_u16 v4, v88 offset:8192
	ds_read_u16 v5, v88 offset:8464
	ds_read_u16 v6, v88 offset:8736
	ds_read_u16 v7, v3 offset:8192
	s_and_b64 vcc, exec, s[38:39]
	s_waitcnt lgkmcnt(3)
	v_lshlrev_b32_e32 v26, 16, v4
	s_waitcnt lgkmcnt(2)
	v_lshlrev_b32_e32 v27, 16, v5
	s_waitcnt lgkmcnt(1)
	v_lshlrev_b32_e32 v28, 16, v6
	s_waitcnt lgkmcnt(0)
	v_lshlrev_b32_e32 v29, 16, v7
	s_cbranch_vccnz .LBB0_400
	s_waitcnt vmcnt(13)
	v_mfma_f32_16x16x32_bf16 v[4:7], v[124:127], v[70:73], v[26:29]
	s_waitcnt vmcnt(12)
	v_mfma_f32_16x16x32_bf16 v[26:29], v[128:131], v[66:69], v[4:7]
.LBB0_400:
	s_nop 4
	v_add_u32_e32 v4, 0xee0, v2
	v_add_u32_e32 v2, 0x1100, v2
	v_add_u32_e32 v87, v95, v4
	ds_read_u16 v4, v3 offset:11728
	ds_read_u16 v5, v87 offset:8192
	ds_read_u16 v6, v87 offset:8464
	v_add_u32_e32 v3, v95, v2
	ds_read_u16 v7, v3 offset:8192
	s_waitcnt lgkmcnt(3)
	v_lshlrev_b32_e32 v22, 16, v4
	s_waitcnt lgkmcnt(2)
	v_lshlrev_b32_e32 v23, 16, v5
	s_waitcnt lgkmcnt(1)
	v_lshlrev_b32_e32 v24, 16, v6
	s_and_b64 vcc, exec, s[38:39]
	s_waitcnt lgkmcnt(0)
	v_lshlrev_b32_e32 v25, 16, v7
	s_cbranch_vccnz .LBB0_402
	s_waitcnt vmcnt(11)
	v_mfma_f32_16x16x32_bf16 v[4:7], v[132:135], v[70:73], v[22:25]
	s_waitcnt vmcnt(10)
	v_mfma_f32_16x16x32_bf16 v[22:25], v[136:139], v[66:69], v[4:7]
.LBB0_402:
	s_nop 4
	v_add_u32_e32 v4, 0xff0, v2
	v_add_u32_e32 v2, 0x1100, v2
	v_add_u32_e32 v86, v95, v4
	ds_read_u16 v4, v3 offset:11728
	ds_read_u16 v5, v3 offset:12000
	ds_read_u16 v6, v86 offset:8192
	v_add_u32_e32 v3, v95, v2
	ds_read_u16 v7, v3 offset:8192
	s_waitcnt lgkmcnt(3)
	v_lshlrev_b32_e32 v18, 16, v4
	s_waitcnt lgkmcnt(2)
	v_lshlrev_b32_e32 v19, 16, v5
	s_waitcnt lgkmcnt(1)
	v_lshlrev_b32_e32 v20, 16, v6
	s_and_b64 vcc, exec, s[38:39]
	s_waitcnt lgkmcnt(0)
	v_lshlrev_b32_e32 v21, 16, v7
	s_cbranch_vccnz .LBB0_404
	s_waitcnt vmcnt(9)
	v_mfma_f32_16x16x32_bf16 v[4:7], v[140:143], v[70:73], v[18:21]
	s_waitcnt vmcnt(8)
	v_mfma_f32_16x16x32_bf16 v[18:21], v[144:147], v[66:69], v[4:7]
.LBB0_404:
	v_add_u32_e32 v2, 0x1100, v2
	v_add_u32_e32 v85, v95, v2
	s_nop 2
	ds_read_u16 v4, v3 offset:11728
	ds_read_u16 v5, v3 offset:12000
	ds_read_u16 v3, v3 offset:12272
	ds_read_u16 v6, v85 offset:8192
	s_and_b64 vcc, exec, s[38:39]
	s_waitcnt lgkmcnt(3)
	v_lshlrev_b32_e32 v14, 16, v4
	s_waitcnt lgkmcnt(2)
	v_lshlrev_b32_e32 v15, 16, v5
	s_waitcnt lgkmcnt(1)
	v_lshlrev_b32_e32 v16, 16, v3
	s_waitcnt lgkmcnt(0)
	v_lshlrev_b32_e32 v17, 16, v6
	s_cbranch_vccnz .LBB0_406
	s_waitcnt vmcnt(7)
	v_mfma_f32_16x16x32_bf16 v[4:7], v[204:207], v[70:73], v[14:17]
	s_waitcnt vmcnt(6)
	v_mfma_f32_16x16x32_bf16 v[14:17], v[208:211], v[66:69], v[4:7]
.LBB0_406:
	v_add_u32_e32 v2, 0x1100, v2
	s_nop 3
	v_add_u32_e32 v6, v95, v2
	ds_read_u16 v3, v85 offset:11728
	ds_read_u16 v4, v85 offset:12000
	ds_read_u16 v5, v85 offset:12272
	ds_read_u16 v6, v6 offset:8192
	s_and_b64 vcc, exec, s[38:39]
	s_waitcnt lgkmcnt(3)
	v_lshlrev_b32_e32 v10, 16, v3
	s_waitcnt lgkmcnt(2)
	v_lshlrev_b32_e32 v11, 16, v4
	s_waitcnt lgkmcnt(1)
	v_lshlrev_b32_e32 v12, 16, v5
	s_waitcnt lgkmcnt(0)
	v_lshlrev_b32_e32 v13, 16, v6
	s_cbranch_vccnz .LBB0_408
	s_waitcnt vmcnt(5)
	v_mfma_f32_16x16x32_bf16 v[4:7], v[212:215], v[70:73], v[10:13]
	s_nop 2
	s_waitcnt vmcnt(4)
	v_mfma_f32_16x16x32_bf16 v[10:13], v[216:219], v[66:69], v[4:7]
.LBB0_408:
	v_add_u32_e32 v3, 0xdd0, v2
	v_add_u32_e32 v2, 0x1100, v2
	v_add_u32_e32 v84, v95, v3
	v_add_u32_e32 v2, v95, v2
	ds_read_u16 v3, v84 offset:8192
	ds_read_u16 v4, v84 offset:8464
	ds_read_u16 v5, v84 offset:8736
	ds_read_u16 v9, v2 offset:8192
	s_and_b64 vcc, exec, s[38:39]
	s_waitcnt lgkmcnt(3)
	v_lshlrev_b32_e32 v6, 16, v3
	s_waitcnt lgkmcnt(2)
	v_lshlrev_b32_e32 v7, 16, v4
	s_waitcnt lgkmcnt(1)
	v_lshlrev_b32_e32 v8, 16, v5
	s_waitcnt lgkmcnt(0)
	v_lshlrev_b32_e32 v9, 16, v9
	s_cbranch_vccnz .LBB0_410
	s_waitcnt vmcnt(3)
	v_mfma_f32_16x16x32_bf16 v[4:7], v[220:223], v[70:73], v[6:9]
	s_waitcnt vmcnt(2)
	v_mfma_f32_16x16x32_bf16 v[6:9], v[224:227], v[66:69], v[4:7]
.LBB0_410:
	ds_read_u16 v3, v2 offset:11728
	s_nop 3
	ds_read_u16 v4, v2 offset:12000
	ds_read_u16 v5, v2 offset:12272
	ds_read_u16 v98, v2 offset:12544
	s_and_b64 vcc, exec, s[38:39]
	s_waitcnt lgkmcnt(3)
	v_lshlrev_b32_e32 v2, 16, v3
	s_waitcnt lgkmcnt(2)
	v_lshlrev_b32_e32 v3, 16, v4
	s_waitcnt lgkmcnt(1)
	v_lshlrev_b32_e32 v4, 16, v5
	s_waitcnt lgkmcnt(0)
	v_lshlrev_b32_e32 v5, 16, v98
	s_cbranch_vccnz .LBB0_412
	s_waitcnt vmcnt(1)
	v_mfma_f32_16x16x32_bf16 v[2:5], v[236:239], v[70:73], v[2:5]
	s_waitcnt vmcnt(0)
	v_mfma_f32_16x16x32_bf16 v[2:5], v[240:243], v[66:69], v[2:5]

; #define LAS __attribute__((address_space(3)))
; __device__ __forceinline__ float logsig16(float x) { return (fminf(x, 0.f) - __logf(1.0f + __expf(-fabsf(x)))) * (1.0f / 16.0f); }
; __device__ void gla_item(const Params& P, int l, int b, int h, int seg, LAS unsigned char* lds) {
;     ...
;             float x[8];
; #pragma unroll
;             for (int j = 0; j < 8; ++j) x[j] = BUP[d8 + j];
; #pragma unroll
;             for (int r = 0; r < 16; ++r) { const float a = ARAW[t_ * 16 + r]; const f32x4 w0 = *(const LAS f32x4*)(WUP + r * 64 + d8), w1 = *(const LAS f32x4*)(WUP + r * 64 + d8 + 4);
; #pragma unroll
;                 for (int j = 0; j < 4; ++j) { x[j] += a * w0[j]; x[4 + j] += a * w1[j]; } }
;             f32x4 o0, o1;
; #pragma unroll
;             for (int j = 0; j < 4; ++j) { o0[j] = logsig16(x[j]); o1[j] = logsig16(x[4 + j]); }
;             *(LAS f32x4*)(LC + t_ * 64 + d8) = o0; *(LAS f32x4*)(LC + t_ * 64 + d8 + 4) = o1;
.LBB0_484:
	s_waitcnt lgkmcnt(0)
	s_barrier
	ds_read_b128 v[170:173], v119 offset:4096
	ds_read_b128 v[174:177], v119 offset:4112
	ds_read_b128 v[178:181], v139 offset:4352
	ds_read_b128 v[182:185], v139 offset:4368
	ds_read_b128 v[186:189], v139 offset:4384
	ds_read_b128 v[190:193], v139 offset:4400
	ds_read_b128 v[204:207], v119
	ds_read_b128 v[208:211], v119 offset:16
	ds_read_b128 v[212:215], v119 offset:256
	ds_read_b128 v[216:219], v119 offset:272
	ds_read_b128 v[220:223], v119 offset:512
	ds_read_b128 v[224:227], v119 offset:528
	ds_read_b128 v[236:239], v119 offset:768
	ds_read_b128 v[240:243], v119 offset:784
	s_waitcnt lgkmcnt(7)
	v_fma_f32 v155, v178, v204, v170
	s_waitcnt lgkmcnt(6)
	v_fma_f32 v174, v178, v208, v174
	v_fma_f32 v168, v178, v205, v171
	v_fma_f32 v175, v178, v209, v175
	v_fma_f32 v172, v178, v206, v172
	v_fma_f32 v176, v178, v210, v176
	v_fmac_f32_e32 v173, v178, v207
	v_fmac_f32_e32 v177, v178, v211
	ds_read_b128 v[204:207], v119 offset:1024
	ds_read_b128 v[208:211], v119 offset:1040
	s_waitcnt lgkmcnt(7)
	v_fmac_f32_e32 v155, v179, v212
	s_waitcnt lgkmcnt(6)
	v_fmac_f32_e32 v174, v179, v216
	v_fmac_f32_e32 v168, v179, v213
	v_fmac_f32_e32 v175, v179, v217
	v_fmac_f32_e32 v172, v179, v214
	v_fmac_f32_e32 v176, v179, v218
	v_fmac_f32_e32 v173, v179, v215
	v_fmac_f32_e32 v177, v179, v219
	ds_read_b128 v[212:215], v119 offset:1280
	ds_read_b128 v[216:219], v119 offset:1296
	s_waitcnt lgkmcnt(7)
	v_fmac_f32_e32 v155, v180, v220
	s_waitcnt lgkmcnt(6)
	v_fmac_f32_e32 v174, v180, v224
	v_fmac_f32_e32 v168, v180, v221
	v_fmac_f32_e32 v175, v180, v225
	v_fmac_f32_e32 v172, v180, v222
	v_fmac_f32_e32 v176, v180, v226
	v_fmac_f32_e32 v173, v180, v223
	v_fmac_f32_e32 v177, v180, v227
	ds_read_b128 v[220:223], v119 offset:1536
	ds_read_b128 v[224:227], v119 offset:1552
	s_waitcnt lgkmcnt(7)
	v_fmac_f32_e32 v155, v181, v236
	s_waitcnt lgkmcnt(6)
	v_fmac_f32_e32 v174, v181, v240
	v_fmac_f32_e32 v168, v181, v237
	v_fmac_f32_e32 v175, v181, v241
	v_fmac_f32_e32 v172, v181, v238
	v_fmac_f32_e32 v176, v181, v242
	v_fmac_f32_e32 v173, v181, v239
	v_fmac_f32_e32 v177, v181, v243
	ds_read_b128 v[178:181], v119 offset:1792
	ds_read_b128 v[236:239], v119 offset:1808
	s_waitcnt lgkmcnt(7)
	v_fmac_f32_e32 v155, v182, v204
	s_waitcnt lgkmcnt(6)
	v_fmac_f32_e32 v174, v182, v208
	v_fmac_f32_e32 v168, v182, v205
	v_fmac_f32_e32 v175, v182, v209
	v_fmac_f32_e32 v172, v182, v206
	v_fmac_f32_e32 v176, v182, v210
	v_fmac_f32_e32 v173, v182, v207
	v_fmac_f32_e32 v177, v182, v211
	ds_read_b128 v[204:207], v119 offset:2048
	ds_read_b128 v[208:211], v119 offset:2064
	s_waitcnt lgkmcnt(7)
	v_fmac_f32_e32 v155, v183, v212
	s_waitcnt lgkmcnt(6)
	v_fmac_f32_e32 v174, v183, v216
	v_fmac_f32_e32 v168, v183, v213
	v_fmac_f32_e32 v175, v183, v217
	v_fmac_f32_e32 v172, v183, v214
	v_fmac_f32_e32 v176, v183, v218
	v_fmac_f32_e32 v173, v183, v215
	v_fmac_f32_e32 v177, v183, v219
	ds_read_b128 v[212:215], v119 offset:2304
	ds_read_b128 v[216:219], v119 offset:2320
	ds_read_b128 v[240:243], v119 offset:2560
	ds_read_b128 v[244:247], v119 offset:2576
	s_waitcnt lgkmcnt(9)
	v_mov_b32_e32 v182, v220
	s_waitcnt lgkmcnt(8)
	v_mov_b32_e32 v170, v227
	s_waitcnt lgkmcnt(7)
	v_mov_b32_e32 v183, v178
	v_pk_mul_f32 v[182:183], v[184:185], v[182:183]
	v_mov_b32_e32 v178, v221
	v_add_f32_e32 v182, v155, v182
	v_add_f32_e32 v155, v182, v183
	v_mov_b32_e32 v182, v224
	s_waitcnt lgkmcnt(6)
	v_mov_b32_e32 v183, v236
	v_pk_mul_f32 v[182:183], v[184:185], v[182:183]
	v_mov_b32_e32 v171, v239
	v_add_f32_e32 v182, v174, v182
	v_add_f32_e32 v239, v182, v183
	v_pk_mul_f32 v[182:183], v[184:185], v[178:179]
	v_mov_b32_e32 v236, v225
	v_add_f32_e32 v182, v168, v182
	v_add_f32_e32 v178, v182, v183
	v_pk_mul_f32 v[182:183], v[184:185], v[236:237]
	v_mov_b32_e32 v227, v238
	v_add_f32_e32 v182, v175, v182
	v_add_f32_e32 v179, v182, v183
	v_mov_b32_e32 v182, v222
	v_mov_b32_e32 v183, v180
	v_pk_mul_f32 v[182:183], v[184:185], v[182:183]
	v_mov_b32_e32 v180, v223
	v_add_f32_e32 v172, v172, v182
	v_add_f32_e32 v236, v172, v183
	v_pk_mul_f32 v[182:183], v[184:185], v[226:227]
	v_pk_mul_f32 v[170:171], v[184:185], v[170:171]
	v_add_f32_e32 v172, v176, v182
	v_add_f32_e32 v237, v172, v183
	v_pk_mul_f32 v[182:183], v[184:185], v[180:181]
	v_add_f32_e32 v170, v177, v170
	v_add_f32_e32 v172, v173, v182
	v_add_f32_e32 v180, v172, v183
	v_add_f32_e32 v226, v170, v171
	ds_read_b128 v[170:173], v119 offset:2816
	ds_read_b128 v[174:177], v119 offset:2832
	ds_read_b128 v[182:185], v119 offset:3072
	ds_read_b128 v[220:223], v119 offset:3088
	s_waitcnt lgkmcnt(8)
	v_mov_b32_e32 v224, v211
	s_waitcnt lgkmcnt(7)
	v_mov_b32_e32 v227, v212
	s_waitcnt lgkmcnt(6)
	v_mov_b32_e32 v225, v219
	v_pk_mul_f32 v[224:225], v[186:187], v[224:225]
	v_mov_b32_e32 v212, v205
	v_add_f32_e32 v219, v226, v224
	v_mov_b32_e32 v226, v204
	v_pk_mul_f32 v[226:227], v[186:187], v[226:227]
	v_mov_b32_e32 v211, v218
	v_add_f32_e32 v204, v155, v226
	v_add_f32_e32 v155, v204, v227
	v_mov_b32_e32 v226, v208
	v_mov_b32_e32 v227, v216
	v_pk_mul_f32 v[226:227], v[186:187], v[226:227]
	v_mov_b32_e32 v216, v209
	v_add_f32_e32 v204, v239, v226
	v_add_f32_e32 v226, v204, v227
	v_pk_mul_f32 v[204:205], v[186:187], v[212:213]
	v_add_f32_e32 v224, v219, v225
	v_add_f32_e32 v204, v178, v204
	v_add_f32_e32 v227, v204, v205
	v_pk_mul_f32 v[204:205], v[186:187], v[216:217]
	s_nop 0
	v_add_f32_e32 v204, v179, v204
	v_add_f32_e32 v178, v204, v205
	v_mov_b32_e32 v204, v206
	v_mov_b32_e32 v205, v214
	v_pk_mul_f32 v[204:205], v[186:187], v[204:205]
	v_mov_b32_e32 v214, v207
	v_add_f32_e32 v204, v236, v204
	v_add_f32_e32 v179, v204, v205
	v_pk_mul_f32 v[204:205], v[186:187], v[210:211]
	v_pk_mul_f32 v[186:187], v[186:187], v[214:215]
	v_add_f32_e32 v204, v237, v204
	v_add_f32_e32 v181, v204, v205
	ds_read_b128 v[204:207], v119 offset:3328
	ds_read_b128 v[208:211], v119 offset:3344
	ds_read_b128 v[212:215], v119 offset:3584
	ds_read_b128 v[216:219], v119 offset:3600
	v_add_f32_e32 v186, v180, v186
	v_add_f32_e32 v180, v186, v187
	s_waitcnt lgkmcnt(8)
; #define LAS __attribute__((address_space(3)))
; __device__ __forceinline__ float logsig16(float x) { return (fminf(x, 0.f) - __logf(1.0f + __expf(-fabsf(x)))) * (1.0f / 16.0f); }
; __device__ void gla_item(const Params& P, int l, int b, int h, int seg, LAS unsigned char* lds) {
;     ...
;             for (int r = 0; r < 16; ++r) { const float a = ARAW[t_ * 16 + r]; const f32x4 w0 = *(const LAS f32x4*)(WUP + r * 64 + d8), w1 = *(const LAS f32x4*)(WUP + r * 64 + d8 + 4);
; #pragma unroll
;                 for (int j = 0; j < 4; ++j) { x[j] += a * w0[j]; x[4 + j] += a * w1[j]; } }
;             f32x4 o0, o1;
; #pragma unroll
;             for (int j = 0; j < 4; ++j) { o0[j] = logsig16(x[j]); o1[j] = logsig16(x[4 + j]); }
;             *(LAS f32x4*)(LC + t_ * 64 + d8) = o0; *(LAS f32x4*)(LC + t_ * 64 + d8 + 4) = o1;
	v_mov_b32_e32 v186, v247
	s_waitcnt lgkmcnt(7)
	v_mov_b32_e32 v225, v170
	s_waitcnt lgkmcnt(6)
	v_mov_b32_e32 v187, v177
	v_pk_mul_f32 v[186:187], v[188:189], v[186:187]
	v_mov_b32_e32 v170, v241
	v_add_f32_e32 v186, v224, v186
	v_mov_b32_e32 v224, v240
	v_pk_mul_f32 v[224:225], v[188:189], v[224:225]
	v_mov_b32_e32 v247, v176
	v_add_f32_e32 v240, v155, v224
	v_add_f32_e32 v155, v240, v225
	v_mov_b32_e32 v224, v244
	v_mov_b32_e32 v225, v174
	v_pk_mul_f32 v[224:225], v[188:189], v[224:225]
	v_mov_b32_e32 v174, v245
	v_add_f32_e32 v240, v226, v224
	v_add_f32_e32 v224, v240, v225
	v_pk_mul_f32 v[240:241], v[188:189], v[170:171]
	v_add_f32_e32 v176, v186, v187
	v_add_f32_e32 v240, v227, v240
	v_add_f32_e32 v225, v240, v241
	v_pk_mul_f32 v[240:241], v[188:189], v[174:175]
	s_nop 0
	v_add_f32_e32 v240, v178, v240
	v_add_f32_e32 v226, v240, v241
	v_mov_b32_e32 v240, v242
	v_mov_b32_e32 v241, v172
	v_pk_mul_f32 v[240:241], v[188:189], v[240:241]
	v_mov_b32_e32 v172, v243
	v_add_f32_e32 v240, v179, v240
	v_add_f32_e32 v227, v240, v241
	v_pk_mul_f32 v[240:241], v[188:189], v[246:247]
	v_pk_mul_f32 v[188:189], v[188:189], v[172:173]
	v_add_f32_e32 v240, v181, v240
	v_add_f32_e32 v188, v180, v188
	v_add_f32_e32 v178, v240, v241
	v_add_f32_e32 v179, v188, v189
	ds_read_b128 v[170:173], v119 offset:3840
	ds_read_b128 v[186:189], v119 offset:3856
	s_nop 0
	s_nop 0
	s_waitcnt lgkmcnt(6)
	v_mov_b32_e32 v174, v223
	s_waitcnt lgkmcnt(5)
	v_mov_b32_e32 v177, v204
	s_waitcnt lgkmcnt(4)
	v_mov_b32_e32 v175, v211
	v_pk_mul_f32 v[174:175], v[190:191], v[174:175]
	v_mov_b32_e32 v204, v183
	v_add_f32_e32 v211, v176, v174
	v_mov_b32_e32 v176, v182
	v_pk_mul_f32 v[176:177], v[190:191], v[176:177]
	v_mov_b32_e32 v223, v210
	v_add_f32_e32 v182, v155, v176
	v_add_f32_e32 v155, v182, v177
	v_mov_b32_e32 v176, v220
	v_mov_b32_e32 v177, v208
	v_pk_mul_f32 v[176:177], v[190:191], v[176:177]
	v_mov_b32_e32 v208, v221
	v_add_f32_e32 v182, v224, v176
	v_add_f32_e32 v176, v182, v177
	v_pk_mul_f32 v[182:183], v[190:191], v[204:205]
	v_add_f32_e32 v174, v211, v175
	v_add_f32_e32 v182, v225, v182
	v_add_f32_e32 v177, v182, v183
	v_pk_mul_f32 v[182:183], v[190:191], v[208:209]
	s_nop 0
	v_add_f32_e32 v182, v226, v182
	v_add_f32_e32 v224, v182, v183
	v_mov_b32_e32 v182, v184
	v_mov_b32_e32 v183, v206
	v_pk_mul_f32 v[182:183], v[190:191], v[182:183]
	v_mov_b32_e32 v206, v185
	v_add_f32_e32 v182, v227, v182
	v_add_f32_e32 v225, v182, v183
	v_pk_mul_f32 v[182:183], v[190:191], v[222:223]
	v_pk_mul_f32 v[190:191], v[190:191], v[206:207]
	v_add_f32_e32 v182, v178, v182
	v_add_f32_e32 v226, v182, v183
	s_nop 0
	s_nop 0
	s_nop 0
	s_nop 0
	v_add_f32_e32 v190, v179, v190
	v_add_f32_e32 v227, v190, v191
	s_waitcnt lgkmcnt(2)
	v_mov_b32_e32 v190, v219
	s_waitcnt lgkmcnt(1)
	v_mov_b32_e32 v175, v170
	s_waitcnt lgkmcnt(0)
	v_mov_b32_e32 v191, v189
	v_pk_mul_f32 v[190:191], v[192:193], v[190:191]
	v_mov_b32_e32 v170, v213
	v_add_f32_e32 v190, v174, v190
	v_mov_b32_e32 v174, v212
	v_pk_mul_f32 v[174:175], v[192:193], v[174:175]
	v_mov_b32_e32 v219, v188
	v_add_f32_e32 v212, v155, v174
	v_add_f32_e32 v189, v212, v175
	v_mov_b32_e32 v174, v216
	v_add_f32_e32 v216, v190, v191
	v_mul_f32_e64 v190, |v189|, s3
	v_exp_f32_e32 v190, v190
	v_mov_b32_e32 v175, v186
	v_pk_mul_f32 v[174:175], v[192:193], v[174:175]
	v_mov_b32_e32 v186, v217
	v_add_f32_e32 v190, 1.0, v190
	v_cmp_gt_f32_e32 vcc, s33, v190
	v_add_f32_e32 v212, v176, v174
	v_add_f32_e32 v174, v212, v175
	v_cndmask_b32_e64 v191, 0, 32, vcc
	v_ldexp_f32 v190, v190, v191
	v_log_f32_e32 v190, v190
	v_pk_mul_f32 v[212:213], v[192:193], v[170:171]
	v_mul_f32_e32 v191, 0x3f317217, v190
	v_fma_f32 v191, v190, s95, -v191
	v_add_f32_e32 v212, v177, v212
	v_fmac_f32_e32 v191, 0x3377d1cf, v190
	v_add_f32_e32 v170, v212, v213
	v_pk_mul_f32 v[212:213], v[192:193], v[186:187]
	v_fmac_f32_e32 v191, 0x3f317217, v190
	v_cmp_lt_f32_e64 s[0:1], |v190|, s27
	v_add_f32_e32 v212, v224, v212
	v_add_f32_e32 v217, v212, v213
	v_cndmask_b32_e64 v190, v190, v191, s[0:1]
	v_cndmask_b32_e32 v191, 0, v233, vcc
	v_mov_b32_e32 v212, v214
	v_sub_f32_e32 v214, v190, v191
	v_mul_f32_e64 v191, |v174|, s3
	v_exp_f32_e32 v191, v191
	v_mov_b32_e32 v213, v172
	v_pk_mul_f32 v[212:213], v[192:193], v[212:213]
	v_mov_b32_e32 v172, v215
	v_add_f32_e32 v212, v225, v212
	v_add_f32_e32 v171, v212, v213
	v_pk_mul_f32 v[212:213], v[192:193], v[218:219]
	v_pk_mul_f32 v[192:193], v[192:193], v[172:173]
	v_mov_b32_e32 v47, v191
	v_mov_b32_e32 v48, v192
	v_mov_b32_e32 v49, v193
	v_mov_b32_e32 v50, v212
	v_mov_b32_e32 v51, v213
	v_mov_b32_e32 v52, v214
	v_mov_b32_e32 v54, v216
	v_mov_b32_e32 v55, v217
	v_mov_b32_e32 v58, v170
	v_mov_b32_e32 v59, v171
	v_mov_b32_e32 v65, v189
	v_mov_b32_e32 v66, v174
	v_mov_b32_e32 v158, v226
	v_mov_b32_e32 v159, v227
	v_add_f32_e32 v47, 1.0, v47
	v_add_f32_e32 v48, v159, v48
	v_cmp_gt_f32_e32 vcc, s33, v47
	v_add_f32_e32 v61, v48, v49
	v_add_f32_e32 v50, v158, v50
	v_cndmask_b32_e64 v49, 0, 32, vcc
	v_ldexp_f32 v47, v47, v49
	v_log_f32_e32 v47, v47
	v_add_f32_e32 v57, v50, v51
; #define LAS __attribute__((address_space(3)))
; #define SEG(src, ld, ktiles, ntiles, n0s, dst, dk, n0d) if (r < (ktiles) * (ntiles)) { const int kt = r / (ntiles), ntl = r % (ntiles); transpose_tile(src, ld, kt * 64, (n0s) + ntl * 64, dst, dk, (n0d) + ntl * 64, tile); continue; } r -= (ktiles) * (ntiles);
; #define LBAR() do { asm volatile("s_waitcnt lgkmcnt(0)" ::: "memory"); __builtin_amdgcn_s_barrier(); asm volatile("" ::: "memory"); } while (0)
; __device__ __forceinline__ float logsig16(float x) { return (fminf(x, 0.f) - __logf(1.0f + __expf(-fabsf(x)))) * (1.0f / 16.0f); }
; __device__ void gla_item(const Params& P, int l, int b, int h, int seg, LAS unsigned char* lds) {
;     ...
;             f32x4 o0, o1;
; #pragma unroll
;             for (int j = 0; j < 4; ++j) { o0[j] = logsig16(x[j]); o1[j] = logsig16(x[4 + j]); }
;             *(LAS f32x4*)(LC + t_ * 64 + d8) = o0; *(LAS f32x4*)(LC + t_ * 64 + d8 + 4) = o1;
;         }
;         LBAR();
;         {
;             const int d = tid & 63, sg = tid >> 6; float cum[8]; float run = 0.f;
; #pragma unroll
;             for (int i = 0; i < 8; ++i) { run += LC[(sg * 8 + i) * 64 + d]; cum[i] = run; }
;             SEG[sg * 64 + d] = run;
;             LBAR();
	v_min_f32_e32 v60, 0, v57
	v_min_f32_e32 v56, 0, v59
	v_mul_f32_e32 v49, 0x3f317217, v47
	v_fma_f32 v49, v47, s95, -v49
	v_fmac_f32_e32 v49, 0x3377d1cf, v47
	v_fmac_f32_e32 v49, 0x3f317217, v47
	v_cmp_lt_f32_e64 s[0:1], |v47|, s27
	v_min_f32_e32 v48, 0, v65
	v_min_f32_e32 v46, 0, v66
	v_cndmask_b32_e64 v47, v47, v49, s[0:1]
	v_cndmask_b32_e32 v49, 0, v233, vcc
	v_sub_f32_e32 v50, v47, v49
	v_mul_f32_e64 v47, |v58|, s3
	v_exp_f32_e32 v47, v47
	v_min_f32_e32 v49, 0, v58
	v_add_f32_e32 v47, 1.0, v47
	v_cmp_gt_f32_e32 vcc, s33, v47
	s_nop 1
	v_cndmask_b32_e64 v51, 0, 32, vcc
	v_ldexp_f32 v47, v47, v51
	v_log_f32_e32 v47, v47
	s_nop 0
	v_mul_f32_e32 v51, 0x3f317217, v47
	v_fma_f32 v51, v47, s95, -v51
	v_fmac_f32_e32 v51, 0x3377d1cf, v47
	v_fmac_f32_e32 v51, 0x3f317217, v47
	v_cmp_lt_f32_e64 s[0:1], |v47|, s27
	s_nop 1
	v_cndmask_b32_e64 v47, v47, v51, s[0:1]
	v_cndmask_b32_e32 v51, 0, v233, vcc
	v_sub_f32_e32 v53, v47, v51
	v_mul_f32_e64 v51, |v55|, s3
	v_exp_f32_e32 v51, v51
	v_min_f32_e32 v47, 0, v55
	v_pk_add_f32 v[48:49], v[48:49], v[52:53] neg_lo:[0,1] neg_hi:[0,1]
	v_add_f32_e32 v51, 1.0, v51
	v_cmp_gt_f32_e32 vcc, s33, v51
	s_nop 1
	v_cndmask_b32_e64 v55, 0, 32, vcc
	v_ldexp_f32 v51, v51, v55
	v_log_f32_e32 v51, v51
	s_nop 0
	v_mul_f32_e32 v55, 0x3f317217, v51
	v_fma_f32 v55, v51, s95, -v55
	v_fmac_f32_e32 v55, 0x3377d1cf, v51
	v_fmac_f32_e32 v55, 0x3f317217, v51
	v_cmp_lt_f32_e64 s[0:1], |v51|, s27
	s_nop 1
	v_cndmask_b32_e64 v51, v51, v55, s[0:1]
	v_cndmask_b32_e32 v55, 0, v233, vcc
	v_sub_f32_e32 v51, v51, v55
	v_mul_f32_e64 v55, |v59|, s3
	v_exp_f32_e32 v55, v55
	v_pk_add_f32 v[46:47], v[46:47], v[50:51] neg_lo:[0,1] neg_hi:[0,1]
	v_add_f32_e32 v55, 1.0, v55
	v_cmp_gt_f32_e32 vcc, s33, v55
	v_pk_mul_f32 v[46:47], v[46:47], s[34:35] op_sel_hi:[1,0]
	s_nop 0
	v_cndmask_b32_e64 v58, 0, 32, vcc
	v_ldexp_f32 v55, v55, v58
	v_log_f32_e32 v55, v55
	s_nop 0
	v_mul_f32_e32 v58, 0x3f317217, v55
	v_fma_f32 v58, v55, s95, -v58
	v_fmac_f32_e32 v58, 0x3377d1cf, v55
	v_fmac_f32_e32 v58, 0x3f317217, v55
	v_cmp_lt_f32_e64 s[0:1], |v55|, s27
	s_nop 1
	v_cndmask_b32_e64 v55, v55, v58, s[0:1]
	v_cndmask_b32_e32 v58, 0, v233, vcc
	v_sub_f32_e32 v58, v55, v58
	v_mul_f32_e64 v55, |v57|, s3
	v_exp_f32_e32 v55, v55
	s_nop 0
	v_add_f32_e32 v55, 1.0, v55
	v_cmp_gt_f32_e32 vcc, s33, v55
	s_nop 1
	v_cndmask_b32_e64 v57, 0, 32, vcc
	v_ldexp_f32 v55, v55, v57
	v_log_f32_e32 v55, v55
	s_nop 0
	v_mul_f32_e32 v57, 0x3f317217, v55
	v_fma_f32 v57, v55, s95, -v57
	v_fmac_f32_e32 v57, 0x3377d1cf, v55
	v_fmac_f32_e32 v57, 0x3f317217, v55
	v_cmp_lt_f32_e64 s[0:1], |v55|, s27
	s_nop 1
	v_cndmask_b32_e64 v55, v55, v57, s[0:1]
	v_cndmask_b32_e32 v57, 0, v233, vcc
	v_sub_f32_e32 v62, v55, v57
	v_mul_f32_e64 v55, |v61|, s3
	v_exp_f32_e32 v55, v55
	v_min_f32_e32 v57, 0, v61
	v_min_f32_e32 v61, 0, v54
	v_add_f32_e32 v55, 1.0, v55
	v_cmp_gt_f32_e32 vcc, s33, v55
	s_nop 1
	v_cndmask_b32_e64 v59, 0, 32, vcc
	v_ldexp_f32 v55, v55, v59
	v_log_f32_e32 v55, v55
	s_nop 0
	v_mul_f32_e32 v59, 0x3f317217, v55
	v_fma_f32 v59, v55, s95, -v59
	v_fmac_f32_e32 v59, 0x3377d1cf, v55
	v_fmac_f32_e32 v59, 0x3f317217, v55
	v_cmp_lt_f32_e64 s[0:1], |v55|, s27
	s_nop 1
	v_cndmask_b32_e64 v55, v55, v59, s[0:1]
	v_cndmask_b32_e32 v59, 0, v233, vcc
	v_sub_f32_e32 v59, v55, v59
	v_pk_add_f32 v[52:53], v[56:57], v[58:59] neg_lo:[0,1] neg_hi:[0,1]
	v_pk_mul_f32 v[56:57], v[48:49], s[34:35] op_sel_hi:[1,0]
	v_mul_f32_e64 v48, |v54|, s3
	v_exp_f32_e32 v48, v48
	v_pk_mul_f32 v[58:59], v[52:53], s[34:35] op_sel_hi:[1,0]
	v_mov_b32_e32 v54, 0
	v_mov_b32_e32 v55, 0
	v_add_f32_e32 v48, 1.0, v48
	v_cmp_gt_f32_e32 vcc, s33, v48
	s_nop 1
	v_cndmask_b32_e64 v49, 0, 32, vcc
	v_ldexp_f32 v48, v48, v49
	v_log_f32_e32 v48, v48
	s_nop 0
	v_mul_f32_e32 v49, 0x3f317217, v48
	v_fma_f32 v49, v48, s95, -v49
	v_fmac_f32_e32 v49, 0x3377d1cf, v48
	v_fmac_f32_e32 v49, 0x3f317217, v48
	v_cmp_lt_f32_e64 s[0:1], |v48|, s27
	s_nop 1
	v_cndmask_b32_e64 v48, v48, v49, s[0:1]
	v_cndmask_b32_e32 v49, 0, v233, vcc
	v_sub_f32_e32 v63, v48, v49
	v_pk_add_f32 v[48:49], v[60:61], v[62:63] neg_lo:[0,1] neg_hi:[0,1]
	s_nop 0
	v_pk_mul_f32 v[48:49], v[48:49], s[34:35] op_sel_hi:[1,0]
	ds_write_b128 v151, v[56:59] offset:8448
	ds_write_b128 v151, v[46:49] offset:8464
	s_waitcnt lgkmcnt(0)
	s_barrier
	ds_read2st64_b32 v[46:47], v152 offset0:33 offset1:34
	ds_read2st64_b32 v[48:49], v152 offset0:35 offset1:36
	ds_read2st64_b32 v[50:51], v152 offset0:37 offset1:38
	ds_read2st64_b32 v[52:53], v152 offset0:39 offset1:40
	s_waitcnt lgkmcnt(3)
	v_add_f32_e32 v46, 0, v46
	v_add_f32_e32 v47, v46, v47
	s_waitcnt lgkmcnt(2)
	v_add_f32_e32 v48, v47, v48
	v_add_f32_e32 v49, v48, v49
	s_waitcnt lgkmcnt(1)
	v_add_f32_e32 v50, v49, v50
	v_add_f32_e32 v51, v50, v51
	s_waitcnt lgkmcnt(0)
	v_add_f32_e32 v52, v51, v52
	v_add_f32_e32 v53, v52, v53
	ds_write_b32 v118, v53 offset:24832
	s_waitcnt lgkmcnt(0)
	s_barrier
	s_and_saveexec_b64 s[0:1], s[40:41]
	s_cbranch_execnz .LBB0_507
	s_or_b64 exec, exec, s[0:1]
	v_mov_b32_e32 v56, 0
	s_and_saveexec_b64 s[0:1], s[42:43]
	s_cbranch_execnz .LBB0_508

; __device__ void gla_item(const Params& P, int l, int b, int h, int seg, LAS unsigned char* lds) {
;     ...
;             for (int jj = 0; jj < 4; ++jj) { const int i = it * 16 + 4 * g + jj, j = jt * 16 + c; const float v = (j <= i) ? A[jj] : 0.f;
;                 *(LAS unsigned short*)(AIN + i * QS + j * 2) = f2bf(v); }
;         }
;         LBAR();
;         bf16x8 Vb[2];
; #pragma unroll
;         for (int ks = 0; ks < 2; ++ks) { unsigned short e[8];
; #pragma unroll
;             for (int j = 0; j < 8; ++j) e[j] = *(const LAS unsigned short*)(VS + (ks * 32 + 8 * g + j) * VSS + (16 * w + c) * 2);
;             u32x4 pw; pw.x = e[0] | ((unsigned)e[1] << 16); pw.y = e[2] | ((unsigned)e[3] << 16); pw.z = e[4] | ((unsigned)e[5] << 16); pw.w = e[6] | ((unsigned)e[7] << 16); Vb[ks] = as_bf16x8(pw); }
;         bf16x8 Sb[2];
; #pragma unroll
;         for (int k2 = 0; k2 < 2; ++k2) { u32x4 pw; pw.x = cvt_pk_bf16(Sacc[2 * k2][0], Sacc[2 * k2][1]); pw.y = cvt_pk_bf16(Sacc[2 * k2][2], Sacc[2 * k2][3]);
;             pw.z = cvt_pk_bf16(Sacc[2 * k2 + 1][0], Sacc[2 * k2 + 1][1]); pw.w = cvt_pk_bf16(Sacc[2 * k2 + 1][2], Sacc[2 * k2 + 1][3]); Sb[k2] = as_bf16x8(pw); }
;         f32x4 Oacc[4];
; #pragma unroll
;         for (int it = 0; it < 4; ++it) {
;             Oacc[it] = (f32x4){0.f, 0.f, 0.f, 0.f};
; #pragma unroll
;             for (int ks = 0; ks < 2; ++ks) { const bf16x8 a = *(const LAS bf16x8*)(AIN + (it * 16 + c) * QS + (ks * 32 + 8 * g) * 2); Oacc[it] = __builtin_amdgcn_mfma_f32_16x16x32_bf16(a, Vb[ks], Oacc[it], 0, 0, 0); }
; #pragma unroll
;             for (int k2 = 0; k2 < 2; ++k2) { const u32x2 lo = *(const LAS u32x2*)(QP + (it * 16 + c) * QS + (32 * k2 + 4 * g) * 2), hi = *(const LAS u32x2*)(QP + (it * 16 + c) * QS + (32 * k2 + 16 + 4 * g) * 2);
;                 const bf16x8 a = as_bf16x8((u32x4){lo.x, lo.y, hi.x, hi.y}); Oacc[it] = __builtin_amdgcn_mfma_f32_16x16x32_bf16(a, Sb[k2], Oacc[it], 0, 0, 0); }
;         }
; #pragma unroll
;         for (int dt = 0; dt < 4; ++dt) {
;             const f32x4 dc = *(const LAS f32x4*)(DEC + dt * 16 + 4 * g);
;             Sacc[dt] = Sacc[dt] * dc;
; #pragma unroll
;             for (int ks = 0; ks < 2; ++ks) { unsigned short e[8];
; #pragma unroll
;                 for (int j = 0; j < 8; ++j) e[j] = *(const LAS unsigned short*)(KPP + (ks * 32 + 8 * g + j) * QS + (dt * 16 + c) * 2);
.LBB0_502:
	s_nop 7
	v_cndmask_b32_e64 v38, v38, 0, s[62:63]
	v_cvt_pk_bf16_f32 v38, v38, v195
	ds_write_b16 v143, v38 offset:56832
	v_cndmask_b32_e64 v38, v39, 0, s[64:65]
	v_cvt_pk_bf16_f32 v38, v38, v195
	ds_write_b16 v143, v38 offset:56976
	v_cndmask_b32_e64 v38, v40, 0, s[66:67]
	v_cvt_pk_bf16_f32 v38, v38, v195
	ds_write_b16 v143, v38 offset:57120
	v_cndmask_b32_e64 v38, v41, 0, s[68:69]
	v_cvt_pk_bf16_f32 v38, v38, v195
	ds_write_b16 v143, v38 offset:57264
	v_add_u32_e32 v236, 0x7000, v146
	v_add_u32_e32 v237, 0x7800, v146
	v_add_u32_e32 v238, 0x8000, v146
	v_add_u32_e32 v239, 0x8800, v146
	v_add_u32_e32 v240, v128, v129
	v_add_u32_e32 v241, v128, v127
	v_add_u32_e32 v242, v128, v130
	v_add_u32_e32 v243, v131, v129
	v_add_u32_e32 v244, v131, v127
	v_add_u32_e32 v245, v131, v130
	v_add_u32_e32 v246, v132, v129
	v_add_u32_e32 v247, v132, v127
	v_add_u32_e32 v248, v132, v130
	v_add_u32_e32 v249, v133, v129
	v_add_u32_e32 v228, v133, v127
	v_add_u32_e32 v229, v133, v130
	s_waitcnt lgkmcnt(0)
	s_barrier
	v_add_u32_e32 v164, v124, v126
	ds_read_u16 v227, v144
	ds_read_u16 v226, v145
	ds_read_u16 v225, v145 offset:272
	ds_read_u16 v224, v145 offset:544
	ds_read_u16 v223, v145 offset:816
	ds_read_u16 v222, v145 offset:1088
	ds_read_u16 v221, v145 offset:1360
	ds_read_u16 v220, v145 offset:1632
	ds_read_u16 v219, v145 offset:8432
	ds_read_u16 v218, v145 offset:8704
	ds_read_u16 v217, v145 offset:8976
	ds_read_u16 v216, v145 offset:9248
	ds_read_u16 v215, v145 offset:9520
	ds_read_u16 v214, v145 offset:9792
	ds_read_u16 v213, v145 offset:10064
	ds_read_u16 v212, v145 offset:10336
	ds_read_b128 v[168:171], v164 offset:56832
	ds_read_b128 v[172:175], v164 offset:56896
	ds_read2_b64 v[176:179], v236 offset0:64 offset1:68
	ds_read_b128 v[180:183], v164 offset:61504
	ds_read2_b64 v[184:187], v236 offset0:72 offset1:76
	ds_read_b128 v[188:191], v164 offset:59200
	v_cvt_pk_bf16_f32 v66, v14, v15
	v_cvt_pk_bf16_f32 v67, v16, v17
	v_cvt_pk_bf16_f32 v68, v22, v23
	v_cvt_pk_bf16_f32 v69, v24, v25
	v_cvt_pk_bf16_f32 v156, v18, v19
	v_cvt_pk_bf16_f32 v157, v20, v21
	v_cvt_pk_bf16_f32 v158, v34, v35
	v_cvt_pk_bf16_f32 v159, v36, v37
	ds_read_b128 v[204:207], v164 offset:59136
	ds_read2_b64 v[208:211], v237 offset0:96 offset1:100
	s_nop 0
	v_perm_b32 v57, v220, v221, s92
	v_perm_b32 v56, v222, v223, s92
	v_perm_b32 v55, v224, v225, s92
	v_perm_b32 v54, v226, v227, s92
	s_andn2_b64 vcc, exec, s[30:31]
	s_waitcnt lgkmcnt(7)
	v_mfma_f32_16x16x32_bf16 v[42:45], v[168:171], v[54:57], 0
	v_perm_b32 v41, v212, v213, s92
	v_perm_b32 v40, v214, v215, s92
	v_perm_b32 v39, v216, v217, s92
	v_perm_b32 v38, v218, v219, s92
	s_nop 0
	s_nop 0
	s_waitcnt lgkmcnt(6)
	v_mfma_f32_16x16x32_bf16 v[42:45], v[172:175], v[38:41], v[42:45]
	ds_read2_b64 v[168:171], v237 offset0:104 offset1:108
	ds_read_b128 v[172:175], v164 offset:61440
	s_waitcnt lgkmcnt(7)
	v_mfma_f32_16x16x32_bf16 v[42:45], v[176:179], v[66:69], v[42:45]
	ds_read2_b64 v[176:179], v238 offset0:128 offset1:132
	ds_read2_b64 v[212:215], v238 offset0:136 offset1:140
	s_waitcnt lgkmcnt(7)
	v_mfma_f32_16x16x32_bf16 v[42:45], v[184:187], v[156:159], v[42:45]
	ds_read_b128 v[184:187], v164 offset:63744
	s_waitcnt lgkmcnt(6)
	v_mfma_f32_16x16x32_bf16 v[58:61], v[204:207], v[54:57], 0
	v_mfma_f32_16x16x32_bf16 v[58:61], v[188:191], v[38:41], v[58:61]
	ds_read_b128 v[188:191], v164 offset:63808
	s_waitcnt lgkmcnt(6)
	v_mfma_f32_16x16x32_bf16 v[58:61], v[208:211], v[66:69], v[58:61]
	ds_read2_b64 v[204:207], v239 offset0:160 offset1:164
	s_nop 0
	s_waitcnt lgkmcnt(6)
	v_mfma_f32_16x16x32_bf16 v[58:61], v[168:171], v[156:159], v[58:61]
	ds_read2_b64 v[168:171], v239 offset0:168 offset1:172
	s_waitcnt lgkmcnt(6)
	v_mfma_f32_16x16x32_bf16 v[62:65], v[172:175], v[54:57], 0
	v_mfma_f32_16x16x32_bf16 v[62:65], v[180:183], v[38:41], v[62:65]
	ds_read_u16 v227, v240 offset:47616
	s_waitcnt lgkmcnt(6)
	v_mfma_f32_16x16x32_bf16 v[62:65], v[176:179], v[66:69], v[62:65]
	ds_read_b128 v[172:175], v124 offset:26880
	s_nop 0
	s_waitcnt lgkmcnt(6)
	v_mfma_f32_16x16x32_bf16 v[62:65], v[212:215], v[156:159], v[62:65]
	ds_read_u16 v226, v241 offset:43152
	ds_read_u16 v225, v241 offset:43296
	s_waitcnt lgkmcnt(7)
	v_mfma_f32_16x16x32_bf16 v[160:163], v[184:187], v[54:57], 0
	s_waitcnt lgkmcnt(6)
	v_mfma_f32_16x16x32_bf16 v[160:163], v[188:191], v[38:41], v[160:163]
	ds_read_u16 v224, v241 offset:43440
	s_waitcnt lgkmcnt(6)
	v_mfma_f32_16x16x32_bf16 v[66:69], v[204:207], v[66:69], v[160:163]
	s_nop 4
	ds_read_u16 v223, v241 offset:43584
	s_nop 0
	ds_read_u16 v222, v241 offset:43728
	s_waitcnt lgkmcnt(7)
	v_mfma_f32_16x16x32_bf16 v[66:69], v[168:171], v[156:159], v[66:69]
	ds_read_u16 v221, v242 offset:47616
	s_nop 0
	s_nop 0
	s_waitcnt lgkmcnt(6)
	v_pk_mul_f32 v[16:17], v[16:17], v[174:175]
	v_pk_mul_f32 v[14:15], v[14:15], v[172:173]
	ds_read_u16 v220, v242 offset:47760
	ds_read_u16 v219, v241 offset:47616
	ds_read_u16 v218, v242 offset:51504
	ds_read_u16 v217, v242 offset:51648
	ds_read_u16 v216, v242 offset:51792
	ds_read_u16 v215, v242 offset:51936
	ds_read_u16 v214, v242 offset:52080
	s_waitcnt lgkmcnt(12)
	v_perm_b32 v156, v226, v227, s92
	s_waitcnt lgkmcnt(10)
	v_perm_b32 v157, v224, v225, s92
	s_waitcnt lgkmcnt(8)
	v_perm_b32 v158, v222, v223, s92
	s_waitcnt lgkmcnt(6)
	v_perm_b32 v159, v220, v221, s92
	s_nop 1
	v_mfma_f32_16x16x32_bf16 v[14:17], v[156:159], v[54:57], v[14:17]
	ds_read_u16 v227, v242 offset:52224
	ds_read_u16 v226, v242 offset:52368
	ds_read_b128 v[168:171], v124 offset:26944
	ds_read_u16 v225, v243 offset:47616
	ds_read_u16 v224, v244 offset:43152
	ds_read_u16 v223, v244 offset:43296
	ds_read_u16 v222, v244 offset:43440
	ds_read_u16 v221, v244 offset:43584
	s_waitcnt lgkmcnt(10)
; #define LAS __attribute__((address_space(3)))
; __device__ __forceinline__ unsigned short f2bf(float f) { return (unsigned short)(cvt_pk_bf16(f, 0.f) & 0xffffu); }
; #define LBAR() do { asm volatile("s_waitcnt lgkmcnt(0)" ::: "memory"); __builtin_amdgcn_s_barrier(); asm volatile("" ::: "memory"); } while (0)
; __device__ void gla_item(const Params& P, int l, int b, int h, int seg, LAS unsigned char* lds) {
;     ...
; #pragma unroll
;         for (int dt = 0; dt < 4; ++dt) {
;             const f32x4 dc = *(const LAS f32x4*)(DEC + dt * 16 + 4 * g);
;             Sacc[dt] = Sacc[dt] * dc;
; #pragma unroll
;             for (int ks = 0; ks < 2; ++ks) { unsigned short e[8];
; #pragma unroll
;                 for (int j = 0; j < 8; ++j) e[j] = *(const LAS unsigned short*)(KPP + (ks * 32 + 8 * g + j) * QS + (dt * 16 + c) * 2);
;                 u32x4 pw; pw.x = e[0] | ((unsigned)e[1] << 16); pw.y = e[2] | ((unsigned)e[3] << 16); pw.z = e[4] | ((unsigned)e[5] << 16); pw.w = e[6] | ((unsigned)e[7] << 16);
;                 Sacc[dt] = __builtin_amdgcn_mfma_f32_16x16x32_bf16(as_bf16x8(pw), Vb[ks], Sacc[dt], 0, 0, 0); }
;         }
; #pragma unroll
;         for (int it = 0; it < 4; ++it)
; #pragma unroll
;             for (int jj = 0; jj < 4; ++jj) *(LAS unsigned short*)(OT + (it * 16 + 4 * g + jj) * VSS + (16 * w + c) * 2) = f2bf(Oacc[it][jj]);
;         LBAR();
;         {
;             const u32x4 o0 = *(const LAS u32x4*)(OT + (tid >> 4) * VSS + (tid & 15) * 16), o1 = *(const LAS u32x4*)(OT + (32 + (tid >> 4)) * VSS + (tid & 15) * 16);
;             *(u32x4*)(Z + (size_t)(row0 + (tid >> 4)) * ZC + ZV + h * 128 + (tid & 15) * 8) = o0;
;             *(u32x4*)(Z + (size_t)(row0 + 32 + (tid >> 4)) * ZC + ZV + h * 128 + (tid & 15) * 8) = o1;
	v_perm_b32 v157, v216, v217, s92
	v_perm_b32 v156, v218, v219, s92
	s_waitcnt lgkmcnt(8)
	v_perm_b32 v158, v214, v215, s92
	s_nop 0
	s_waitcnt lgkmcnt(6)
	v_perm_b32 v159, v226, v227, s92
	s_nop 0
	s_nop 0
	v_mfma_f32_16x16x32_bf16 v[14:17], v[156:159], v[38:41], v[14:17]
	ds_read_u16 v227, v244 offset:43728
	ds_read_u16 v226, v245 offset:47616
	s_waitcnt lgkmcnt(7)
	v_pk_mul_f32 v[24:25], v[24:25], v[170:171]
	v_pk_mul_f32 v[22:23], v[22:23], v[168:169]
	ds_read_u16 v220, v245 offset:47760
	ds_read_u16 v219, v244 offset:47616
	ds_read_u16 v218, v245 offset:51504
	ds_read_u16 v217, v245 offset:51648
	ds_read_u16 v216, v245 offset:51792
	ds_read_u16 v215, v245 offset:51936
	ds_read_u16 v214, v245 offset:52080
	s_waitcnt lgkmcnt(12)
	v_perm_b32 v156, v224, v225, s92
	s_waitcnt lgkmcnt(10)
	v_perm_b32 v157, v222, v223, s92
	s_waitcnt lgkmcnt(8)
	v_perm_b32 v158, v227, v221, s92
	s_waitcnt lgkmcnt(6)
	v_perm_b32 v159, v220, v226, s92
	s_nop 1
	v_mfma_f32_16x16x32_bf16 v[22:25], v[156:159], v[54:57], v[22:25]
	ds_read_u16 v227, v245 offset:52224
	ds_read_u16 v226, v245 offset:52368
	ds_read_b128 v[168:171], v124 offset:27008
	ds_read_u16 v225, v246 offset:47616
	ds_read_u16 v224, v247 offset:43152
	ds_read_u16 v223, v247 offset:43296
	ds_read_u16 v222, v247 offset:43440
	ds_read_u16 v221, v247 offset:43584
	s_waitcnt lgkmcnt(10)
	v_perm_b32 v157, v216, v217, s92
	v_perm_b32 v156, v218, v219, s92
	s_waitcnt lgkmcnt(8)
	v_perm_b32 v158, v214, v215, s92
	s_nop 0
	s_waitcnt lgkmcnt(6)
	v_perm_b32 v159, v226, v227, s92
	s_nop 0
	s_nop 0
	v_mfma_f32_16x16x32_bf16 v[22:25], v[156:159], v[38:41], v[22:25]
	ds_read_u16 v227, v247 offset:43728
	ds_read_u16 v226, v248 offset:47616
	s_waitcnt lgkmcnt(7)
	v_pk_mul_f32 v[20:21], v[20:21], v[170:171]
	v_pk_mul_f32 v[18:19], v[18:19], v[168:169]
	ds_read_u16 v220, v248 offset:47760
	ds_read_u16 v219, v247 offset:47616
	ds_read_u16 v218, v248 offset:51504
	ds_read_u16 v217, v248 offset:51648
	ds_read_u16 v216, v248 offset:51792
	ds_read_u16 v215, v248 offset:51936
	ds_read_u16 v214, v248 offset:52080
	s_waitcnt lgkmcnt(12)
	v_perm_b32 v156, v224, v225, s92
	s_waitcnt lgkmcnt(10)
	v_perm_b32 v157, v222, v223, s92
	s_waitcnt lgkmcnt(8)
	v_perm_b32 v158, v227, v221, s92
	s_waitcnt lgkmcnt(6)
	v_perm_b32 v159, v220, v226, s92
	s_nop 1
	v_mfma_f32_16x16x32_bf16 v[18:21], v[156:159], v[54:57], v[18:21]
	ds_read_u16 v227, v248 offset:52224
	ds_read_u16 v226, v248 offset:52368
	ds_read_b128 v[168:171], v124 offset:27072
	ds_read_u16 v225, v249 offset:47616
	ds_read_u16 v224, v228 offset:43152
	ds_read_u16 v223, v228 offset:43296
	ds_read_u16 v222, v228 offset:43440
	ds_read_u16 v221, v228 offset:43584
	s_waitcnt lgkmcnt(10)
	v_perm_b32 v157, v216, v217, s92
	v_perm_b32 v156, v218, v219, s92
	s_waitcnt lgkmcnt(8)
	v_perm_b32 v158, v214, v215, s92
	s_nop 0
	s_waitcnt lgkmcnt(6)
	v_perm_b32 v159, v226, v227, s92
	s_nop 0
	s_nop 0
	v_mfma_f32_16x16x32_bf16 v[18:21], v[156:159], v[38:41], v[18:21]
	ds_read_u16 v227, v228 offset:43728
	ds_read_u16 v226, v229 offset:47616
	s_waitcnt lgkmcnt(7)
	v_pk_mul_f32 v[36:37], v[36:37], v[170:171]
	v_pk_mul_f32 v[34:35], v[34:35], v[168:169]
	ds_read_u16 v220, v229 offset:47760
	ds_read_u16 v219, v228 offset:47616
	ds_read_u16 v218, v229 offset:51504
	ds_read_u16 v217, v229 offset:51648
	ds_read_u16 v216, v229 offset:51792
	ds_read_u16 v215, v229 offset:51936
	ds_read_u16 v214, v229 offset:52080
	s_waitcnt lgkmcnt(12)
	v_perm_b32 v156, v224, v225, s92
	s_waitcnt lgkmcnt(10)
	v_perm_b32 v157, v222, v223, s92
	s_waitcnt lgkmcnt(8)
	v_perm_b32 v158, v227, v221, s92
	s_waitcnt lgkmcnt(6)
	v_perm_b32 v159, v220, v226, s92
	s_nop 1
	v_mfma_f32_16x16x32_bf16 v[34:37], v[156:159], v[54:57], v[34:37]
	ds_read_u16 v227, v229 offset:52224
	ds_read_u16 v226, v229 offset:52368
	s_nop 0
	s_nop 0
	s_nop 0
	s_nop 0
	s_nop 0
	s_nop 0
	s_waitcnt lgkmcnt(4)
	v_perm_b32 v55, v216, v217, s92
	v_perm_b32 v54, v218, v219, s92
	s_waitcnt lgkmcnt(2)
	v_perm_b32 v56, v214, v215, s92
	s_waitcnt lgkmcnt(0)
	v_perm_b32 v57, v226, v227, s92
	s_nop 1
	v_mfma_f32_16x16x32_bf16 v[34:37], v[54:57], v[38:41], v[34:37]
	v_mov_b32_e32 v166, v206
	v_mov_b32_e32 v167, v207
	v_cvt_pk_bf16_f32 v38, v42, v195
	ds_write_b16 v147, v38
	v_cvt_pk_bf16_f32 v38, v43, v195
	ds_write_b16 v148, v38
	v_cvt_pk_bf16_f32 v38, v44, v195
	ds_write_b16 v148, v38 offset:272
	v_cvt_pk_bf16_f32 v38, v45, v195
	ds_write_b16 v148, v38 offset:544
	v_cvt_pk_bf16_f32 v38, v58, v195
	ds_write_b16 v148, v38 offset:4080
	v_cvt_pk_bf16_f32 v38, v59, v195
	ds_write_b16 v148, v38 offset:4352
	v_cvt_pk_bf16_f32 v38, v60, v195
	ds_write_b16 v148, v38 offset:4624
	v_cvt_pk_bf16_f32 v38, v61, v195
	ds_write_b16 v148, v38 offset:4896
	v_cvt_pk_bf16_f32 v38, v62, v195
	ds_write_b16 v148, v38 offset:8432
	v_cvt_pk_bf16_f32 v38, v63, v195
	ds_write_b16 v148, v38 offset:8704
	v_cvt_pk_bf16_f32 v38, v64, v195
	ds_write_b16 v148, v38 offset:8976
	v_cvt_pk_bf16_f32 v38, v65, v195
	ds_write_b16 v148, v38 offset:9248
	v_cvt_pk_bf16_f32 v38, v66, v195
	ds_write_b16 v148, v38 offset:12784
	v_cvt_pk_bf16_f32 v38, v67, v195
	ds_write_b16 v148, v38 offset:13056
	v_cvt_pk_bf16_f32 v38, v68, v195
	ds_write_b16 v148, v38 offset:13328
	v_cvt_pk_bf16_f32 v38, v69, v195
	ds_write_b16 v148, v38 offset:13600
	s_waitcnt lgkmcnt(0)
	s_barrier
	ds_read_b128 v[38:41], v149
	ds_read_b128 v[42:45], v150 offset:8704
	v_mad_i64_i32 v[54:55], s[0:1], v154, s25, v[108:109]
	s_waitcnt lgkmcnt(1)
	global_store_dwordx4 v[54:55], v[38:41], off offset:1024
	s_nop 1
	v_add_u32_e32 v38, 32, v154
	v_mad_i64_i32 v[38:39], s[0:1], v38, s25, v[108:109]
	s_mov_b64 s[0:1], -1
	s_waitcnt lgkmcnt(0)
	global_store_dwordx4 v[38:39], v[42:45], off offset:1024
	s_cbranch_vccnz .LBB0_504
	s_mov_b64 s[0:1], 0
